# phase 1 big tiles: first half of the MFMAs issued before the second barrier and the LDS-DMA issue (second-half fragment reads overlap them)
# speedup vs baseline: 1.0375x; 1.0068x over previous
.Lbig_k_in:
	s_barrier
	ds_read_b128 v[160:163], v198 offset:0
	ds_read_b128 v[164:167], v198 offset:2048
	ds_read_b128 v[168:171], v198 offset:4096
	ds_read_b128 v[172:175], v198 offset:6144
	ds_read_b128 v[128:131], v196 offset:0
	ds_read_b128 v[132:135], v196 offset:2048
	ds_read_b128 v[136:139], v196 offset:4096
	ds_read_b128 v[140:143], v196 offset:6144
	ds_read_b128 v[144:147], v196 offset:8192
	ds_read_b128 v[148:151], v196 offset:10240
	ds_read_b128 v[152:155], v196 offset:12288
	ds_read_b128 v[156:159], v196 offset:14336
	ds_read_b128 v[176:179], v200 offset:0
	ds_read_b128 v[180:183], v200 offset:2048
	ds_read_b128 v[184:187], v200 offset:4096
	ds_read_b128 v[188:191], v200 offset:6144
	ds_read_b128 v[204:207], v197 offset:0
	ds_read_b128 v[208:211], v197 offset:2048
	ds_read_b128 v[212:215], v197 offset:4096
	ds_read_b128 v[216:219], v197 offset:6144
	ds_read_b128 v[220:223], v197 offset:8192
	ds_read_b128 v[224:227], v197 offset:10240
	ds_read_b128 v[228:231], v197 offset:12288
	ds_read_b128 v[232:235], v197 offset:14336
	s_waitcnt lgkmcnt(12)
	s_setprio 1
	v_mfma_f32_16x16x32_bf16 v[0:3], v[160:163], v[128:131], v[0:3]
	v_mfma_f32_16x16x32_bf16 v[4:7], v[164:167], v[128:131], v[4:7]
	v_mfma_f32_16x16x32_bf16 v[8:11], v[168:171], v[128:131], v[8:11]
	v_mfma_f32_16x16x32_bf16 v[12:15], v[172:175], v[128:131], v[12:15]
	v_mfma_f32_16x16x32_bf16 v[16:19], v[160:163], v[132:135], v[16:19]
	v_mfma_f32_16x16x32_bf16 v[20:23], v[164:167], v[132:135], v[20:23]
	v_mfma_f32_16x16x32_bf16 v[24:27], v[168:171], v[132:135], v[24:27]
	v_mfma_f32_16x16x32_bf16 v[28:31], v[172:175], v[132:135], v[28:31]
	v_mfma_f32_16x16x32_bf16 v[32:35], v[160:163], v[136:139], v[32:35]
	v_mfma_f32_16x16x32_bf16 v[36:39], v[164:167], v[136:139], v[36:39]
	v_mfma_f32_16x16x32_bf16 v[40:43], v[168:171], v[136:139], v[40:43]
	v_mfma_f32_16x16x32_bf16 v[44:47], v[172:175], v[136:139], v[44:47]
	v_mfma_f32_16x16x32_bf16 v[48:51], v[160:163], v[140:143], v[48:51]
	v_mfma_f32_16x16x32_bf16 v[52:55], v[164:167], v[140:143], v[52:55]
	v_mfma_f32_16x16x32_bf16 v[56:59], v[168:171], v[140:143], v[56:59]
	v_mfma_f32_16x16x32_bf16 v[60:63], v[172:175], v[140:143], v[60:63]
	v_mfma_f32_16x16x32_bf16 v[64:67], v[160:163], v[144:147], v[64:67]
	v_mfma_f32_16x16x32_bf16 v[68:71], v[164:167], v[144:147], v[68:71]
	v_mfma_f32_16x16x32_bf16 v[72:75], v[168:171], v[144:147], v[72:75]
	v_mfma_f32_16x16x32_bf16 v[76:79], v[172:175], v[144:147], v[76:79]
	v_mfma_f32_16x16x32_bf16 v[80:83], v[160:163], v[148:151], v[80:83]
	v_mfma_f32_16x16x32_bf16 v[84:87], v[164:167], v[148:151], v[84:87]
	v_mfma_f32_16x16x32_bf16 v[88:91], v[168:171], v[148:151], v[88:91]
	v_mfma_f32_16x16x32_bf16 v[92:95], v[172:175], v[148:151], v[92:95]
	v_mfma_f32_16x16x32_bf16 v[96:99], v[160:163], v[152:155], v[96:99]
	v_mfma_f32_16x16x32_bf16 v[100:103], v[164:167], v[152:155], v[100:103]
	v_mfma_f32_16x16x32_bf16 v[104:107], v[168:171], v[152:155], v[104:107]
	v_mfma_f32_16x16x32_bf16 v[108:111], v[172:175], v[152:155], v[108:111]
	v_mfma_f32_16x16x32_bf16 v[112:115], v[160:163], v[156:159], v[112:115]
	v_mfma_f32_16x16x32_bf16 v[116:119], v[164:167], v[156:159], v[116:119]
	v_mfma_f32_16x16x32_bf16 v[120:123], v[168:171], v[156:159], v[120:123]
	v_mfma_f32_16x16x32_bf16 v[124:127], v[172:175], v[156:159], v[124:127]
	s_setprio 0
	s_waitcnt lgkmcnt(0)
	s_barrier
	s_add_u32 m0, s32, 0x0
	s_nop 0
	global_load_lds_dwordx4 v192, s[36:37]
	s_add_u32 m0, s32, 0x1000
	s_nop 0
	global_load_lds_dwordx4 v193, s[36:37]
	s_add_u32 m0, s32, 0x2000
	s_nop 0
	global_load_lds_dwordx4 v194, s[36:37]
	s_add_u32 m0, s32, 0x3000
	s_nop 0
	global_load_lds_dwordx4 v195, s[36:37]
	s_add_u32 m0, s32, 0x4000
	s_nop 0
	global_load_lds_dwordx4 v192, s[40:41]
	s_add_u32 m0, s32, 0x5000
	s_nop 0
	global_load_lds_dwordx4 v193, s[40:41]
	s_add_u32 m0, s32, 0x6000
	s_nop 0
	global_load_lds_dwordx4 v194, s[40:41]
	s_add_u32 m0, s32, 0x7000
	s_nop 0
	global_load_lds_dwordx4 v195, s[40:41]
	s_add_u32 m0, s32, 0x8000
	s_nop 0
	global_load_lds_dwordx4 v192, s[44:45]
	s_add_u32 m0, s32, 0x9000
	s_nop 0
	global_load_lds_dwordx4 v193, s[44:45]
	s_add_u32 m0, s32, 0xa000
	s_nop 0
	global_load_lds_dwordx4 v194, s[44:45]
	s_add_u32 m0, s32, 0xb000
	s_nop 0
	global_load_lds_dwordx4 v195, s[44:45]
	s_add_u32 s36, s36, 0x80
	s_addc_u32 s37, s37, 0
	s_add_u32 s40, s40, 0x80
	s_addc_u32 s41, s41, 0
	s_add_u32 s44, s44, 0x80
	s_addc_u32 s45, s45, 0
	s_add_i32 s20, s20, 1
	s_cmp_eq_u32 s20, 32
	s_cbranch_scc1 .Lbig_wrap1
.Lbig_wrapret1:
	s_setprio 1
	v_mfma_f32_16x16x32_bf16 v[0:3], v[176:179], v[204:207], v[0:3]
	v_mfma_f32_16x16x32_bf16 v[4:7], v[180:183], v[204:207], v[4:7]
	v_mfma_f32_16x16x32_bf16 v[8:11], v[184:187], v[204:207], v[8:11]
	v_mfma_f32_16x16x32_bf16 v[12:15], v[188:191], v[204:207], v[12:15]
	v_mfma_f32_16x16x32_bf16 v[16:19], v[176:179], v[208:211], v[16:19]
	v_mfma_f32_16x16x32_bf16 v[20:23], v[180:183], v[208:211], v[20:23]
	v_mfma_f32_16x16x32_bf16 v[24:27], v[184:187], v[208:211], v[24:27]
	v_mfma_f32_16x16x32_bf16 v[28:31], v[188:191], v[208:211], v[28:31]
	v_mfma_f32_16x16x32_bf16 v[32:35], v[176:179], v[212:215], v[32:35]
	v_mfma_f32_16x16x32_bf16 v[36:39], v[180:183], v[212:215], v[36:39]
	v_mfma_f32_16x16x32_bf16 v[40:43], v[184:187], v[212:215], v[40:43]
	v_mfma_f32_16x16x32_bf16 v[44:47], v[188:191], v[212:215], v[44:47]
	v_mfma_f32_16x16x32_bf16 v[48:51], v[176:179], v[216:219], v[48:51]
	v_mfma_f32_16x16x32_bf16 v[52:55], v[180:183], v[216:219], v[52:55]
	v_mfma_f32_16x16x32_bf16 v[56:59], v[184:187], v[216:219], v[56:59]
	v_mfma_f32_16x16x32_bf16 v[60:63], v[188:191], v[216:219], v[60:63]
	v_mfma_f32_16x16x32_bf16 v[64:67], v[176:179], v[220:223], v[64:67]
	v_mfma_f32_16x16x32_bf16 v[68:71], v[180:183], v[220:223], v[68:71]
	v_mfma_f32_16x16x32_bf16 v[72:75], v[184:187], v[220:223], v[72:75]
	v_mfma_f32_16x16x32_bf16 v[76:79], v[188:191], v[220:223], v[76:79]
	v_mfma_f32_16x16x32_bf16 v[80:83], v[176:179], v[224:227], v[80:83]
	v_mfma_f32_16x16x32_bf16 v[84:87], v[180:183], v[224:227], v[84:87]
	v_mfma_f32_16x16x32_bf16 v[88:91], v[184:187], v[224:227], v[88:91]
	v_mfma_f32_16x16x32_bf16 v[92:95], v[188:191], v[224:227], v[92:95]
	v_mfma_f32_16x16x32_bf16 v[96:99], v[176:179], v[228:231], v[96:99]
	v_mfma_f32_16x16x32_bf16 v[100:103], v[180:183], v[228:231], v[100:103]
	v_mfma_f32_16x16x32_bf16 v[104:107], v[184:187], v[228:231], v[104:107]
	v_mfma_f32_16x16x32_bf16 v[108:111], v[188:191], v[228:231], v[108:111]
	v_mfma_f32_16x16x32_bf16 v[112:115], v[176:179], v[232:235], v[112:115]
	v_mfma_f32_16x16x32_bf16 v[116:119], v[180:183], v[232:235], v[116:119]
	v_mfma_f32_16x16x32_bf16 v[120:123], v[184:187], v[232:235], v[120:123]
	v_mfma_f32_16x16x32_bf16 v[124:127], v[188:191], v[232:235], v[124:127]
	s_setprio 0
	s_add_i32 s50, s50, 1
	s_cmp_lt_u32 s50, 31
	s_cbranch_scc1 .Lbig_k
	s_waitcnt vmcnt(0)
	s_barrier
	ds_read_b128 v[160:163], v198 offset:0
	ds_read_b128 v[164:167], v198 offset:2048
	ds_read_b128 v[168:171], v198 offset:4096
	ds_read_b128 v[172:175], v198 offset:6144
	ds_read_b128 v[128:131], v196 offset:0
	ds_read_b128 v[132:135], v196 offset:2048
	ds_read_b128 v[136:139], v196 offset:4096
	ds_read_b128 v[140:143], v196 offset:6144
	ds_read_b128 v[144:147], v196 offset:8192
	ds_read_b128 v[148:151], v196 offset:10240
	ds_read_b128 v[152:155], v196 offset:12288
	ds_read_b128 v[156:159], v196 offset:14336
	ds_read_b128 v[176:179], v200 offset:0
	ds_read_b128 v[180:183], v200 offset:2048
	ds_read_b128 v[184:187], v200 offset:4096
	ds_read_b128 v[188:191], v200 offset:6144
	ds_read_b128 v[204:207], v197 offset:0
	ds_read_b128 v[208:211], v197 offset:2048
	ds_read_b128 v[212:215], v197 offset:4096
	ds_read_b128 v[216:219], v197 offset:6144
	ds_read_b128 v[220:223], v197 offset:8192
	ds_read_b128 v[224:227], v197 offset:10240
	ds_read_b128 v[228:231], v197 offset:12288
	ds_read_b128 v[232:235], v197 offset:14336
	s_waitcnt lgkmcnt(12)
	s_setprio 1
	v_mfma_f32_16x16x32_bf16 v[0:3], v[160:163], v[128:131], v[0:3]
	v_mfma_f32_16x16x32_bf16 v[4:7], v[164:167], v[128:131], v[4:7]
	v_mfma_f32_16x16x32_bf16 v[8:11], v[168:171], v[128:131], v[8:11]
	v_mfma_f32_16x16x32_bf16 v[12:15], v[172:175], v[128:131], v[12:15]
	v_mfma_f32_16x16x32_bf16 v[16:19], v[160:163], v[132:135], v[16:19]
	v_mfma_f32_16x16x32_bf16 v[20:23], v[164:167], v[132:135], v[20:23]
	v_mfma_f32_16x16x32_bf16 v[24:27], v[168:171], v[132:135], v[24:27]
	v_mfma_f32_16x16x32_bf16 v[28:31], v[172:175], v[132:135], v[28:31]
	v_mfma_f32_16x16x32_bf16 v[32:35], v[160:163], v[136:139], v[32:35]
	v_mfma_f32_16x16x32_bf16 v[36:39], v[164:167], v[136:139], v[36:39]
	v_mfma_f32_16x16x32_bf16 v[40:43], v[168:171], v[136:139], v[40:43]
	v_mfma_f32_16x16x32_bf16 v[44:47], v[172:175], v[136:139], v[44:47]
	v_mfma_f32_16x16x32_bf16 v[48:51], v[160:163], v[140:143], v[48:51]
	v_mfma_f32_16x16x32_bf16 v[52:55], v[164:167], v[140:143], v[52:55]
	v_mfma_f32_16x16x32_bf16 v[56:59], v[168:171], v[140:143], v[56:59]
	v_mfma_f32_16x16x32_bf16 v[60:63], v[172:175], v[140:143], v[60:63]
	v_mfma_f32_16x16x32_bf16 v[64:67], v[160:163], v[144:147], v[64:67]
	v_mfma_f32_16x16x32_bf16 v[68:71], v[164:167], v[144:147], v[68:71]
	v_mfma_f32_16x16x32_bf16 v[72:75], v[168:171], v[144:147], v[72:75]
	v_mfma_f32_16x16x32_bf16 v[76:79], v[172:175], v[144:147], v[76:79]
	v_mfma_f32_16x16x32_bf16 v[80:83], v[160:163], v[148:151], v[80:83]
	v_mfma_f32_16x16x32_bf16 v[84:87], v[164:167], v[148:151], v[84:87]
	v_mfma_f32_16x16x32_bf16 v[88:91], v[168:171], v[148:151], v[88:91]
	v_mfma_f32_16x16x32_bf16 v[92:95], v[172:175], v[148:151], v[92:95]
	v_mfma_f32_16x16x32_bf16 v[96:99], v[160:163], v[152:155], v[96:99]
	v_mfma_f32_16x16x32_bf16 v[100:103], v[164:167], v[152:155], v[100:103]
	v_mfma_f32_16x16x32_bf16 v[104:107], v[168:171], v[152:155], v[104:107]
	v_mfma_f32_16x16x32_bf16 v[108:111], v[172:175], v[152:155], v[108:111]
	v_mfma_f32_16x16x32_bf16 v[112:115], v[160:163], v[156:159], v[112:115]
	v_mfma_f32_16x16x32_bf16 v[116:119], v[164:167], v[156:159], v[116:119]
	v_mfma_f32_16x16x32_bf16 v[120:123], v[168:171], v[156:159], v[120:123]
	v_mfma_f32_16x16x32_bf16 v[124:127], v[172:175], v[156:159], v[124:127]
	s_setprio 0
	s_waitcnt lgkmcnt(0)
	s_cmp_ge_u32 s91, 0x1400
	s_cbranch_scc1 .Lbig_nonext
	s_barrier
	s_mov_b64 s[36:37], s[46:47]
	s_mov_b64 s[44:45], s[48:49]
	s_add_u32 s40, s36, 0x80000
	s_addc_u32 s41, s37, 0
	s_mov_b32 s20, s21
	s_add_u32 m0, s32, 0x0
	s_nop 0
	global_load_lds_dwordx4 v192, s[36:37]
	s_add_u32 m0, s32, 0x1000
	s_nop 0
	global_load_lds_dwordx4 v193, s[36:37]
	s_add_u32 m0, s32, 0x2000
	s_nop 0
	global_load_lds_dwordx4 v194, s[36:37]
	s_add_u32 m0, s32, 0x3000
	s_nop 0
	global_load_lds_dwordx4 v195, s[36:37]
	s_add_u32 m0, s32, 0x4000
	s_nop 0
	global_load_lds_dwordx4 v192, s[40:41]
	s_add_u32 m0, s32, 0x5000
	s_nop 0
	global_load_lds_dwordx4 v193, s[40:41]
	s_add_u32 m0, s32, 0x6000
	s_nop 0
	global_load_lds_dwordx4 v194, s[40:41]
	s_add_u32 m0, s32, 0x7000
	s_nop 0
	global_load_lds_dwordx4 v195, s[40:41]
	s_add_u32 m0, s32, 0x8000
	s_nop 0
	global_load_lds_dwordx4 v192, s[44:45]
	s_add_u32 m0, s32, 0x9000
	s_nop 0
	global_load_lds_dwordx4 v193, s[44:45]
	s_add_u32 m0, s32, 0xa000
	s_nop 0
	global_load_lds_dwordx4 v194, s[44:45]
	s_add_u32 m0, s32, 0xb000
	s_nop 0
	global_load_lds_dwordx4 v195, s[44:45]
	s_add_u32 s36, s36, 0x80
	s_addc_u32 s37, s37, 0
	s_add_u32 s40, s40, 0x80
	s_addc_u32 s41, s41, 0
	s_add_u32 s44, s44, 0x80
	s_addc_u32 s45, s45, 0
	s_add_i32 s20, s20, 1
	s_cmp_eq_u32 s20, 32
	s_cbranch_scc1 .Lbig_wrap2
.Lbig_wrapret2:
.Lbig_nonext:
	s_setprio 1
	v_mfma_f32_16x16x32_bf16 v[0:3], v[176:179], v[204:207], v[0:3]
	v_mfma_f32_16x16x32_bf16 v[4:7], v[180:183], v[204:207], v[4:7]
	v_mfma_f32_16x16x32_bf16 v[8:11], v[184:187], v[204:207], v[8:11]
	v_mfma_f32_16x16x32_bf16 v[12:15], v[188:191], v[204:207], v[12:15]
	v_mfma_f32_16x16x32_bf16 v[16:19], v[176:179], v[208:211], v[16:19]
	v_mfma_f32_16x16x32_bf16 v[20:23], v[180:183], v[208:211], v[20:23]
	v_mfma_f32_16x16x32_bf16 v[24:27], v[184:187], v[208:211], v[24:27]
	v_mfma_f32_16x16x32_bf16 v[28:31], v[188:191], v[208:211], v[28:31]
	v_mfma_f32_16x16x32_bf16 v[32:35], v[176:179], v[212:215], v[32:35]
	v_mfma_f32_16x16x32_bf16 v[36:39], v[180:183], v[212:215], v[36:39]
	v_mfma_f32_16x16x32_bf16 v[40:43], v[184:187], v[212:215], v[40:43]
	v_mfma_f32_16x16x32_bf16 v[44:47], v[188:191], v[212:215], v[44:47]
	v_mfma_f32_16x16x32_bf16 v[48:51], v[176:179], v[216:219], v[48:51]
	v_mfma_f32_16x16x32_bf16 v[52:55], v[180:183], v[216:219], v[52:55]
	v_mfma_f32_16x16x32_bf16 v[56:59], v[184:187], v[216:219], v[56:59]
	v_mfma_f32_16x16x32_bf16 v[60:63], v[188:191], v[216:219], v[60:63]
	v_mfma_f32_16x16x32_bf16 v[64:67], v[176:179], v[220:223], v[64:67]
	v_mfma_f32_16x16x32_bf16 v[68:71], v[180:183], v[220:223], v[68:71]
	v_mfma_f32_16x16x32_bf16 v[72:75], v[184:187], v[220:223], v[72:75]
	v_mfma_f32_16x16x32_bf16 v[76:79], v[188:191], v[220:223], v[76:79]
	v_mfma_f32_16x16x32_bf16 v[80:83], v[176:179], v[224:227], v[80:83]
	v_mfma_f32_16x16x32_bf16 v[84:87], v[180:183], v[224:227], v[84:87]
	v_mfma_f32_16x16x32_bf16 v[88:91], v[184:187], v[224:227], v[88:91]
	v_mfma_f32_16x16x32_bf16 v[92:95], v[188:191], v[224:227], v[92:95]
	v_mfma_f32_16x16x32_bf16 v[96:99], v[176:179], v[228:231], v[96:99]
	v_mfma_f32_16x16x32_bf16 v[100:103], v[180:183], v[228:231], v[100:103]
	v_mfma_f32_16x16x32_bf16 v[104:107], v[184:187], v[228:231], v[104:107]
	v_mfma_f32_16x16x32_bf16 v[108:111], v[188:191], v[228:231], v[108:111]
	v_mfma_f32_16x16x32_bf16 v[112:115], v[176:179], v[232:235], v[112:115]
	v_mfma_f32_16x16x32_bf16 v[116:119], v[180:183], v[232:235], v[116:119]
	v_mfma_f32_16x16x32_bf16 v[120:123], v[184:187], v[232:235], v[120:123]
	v_mfma_f32_16x16x32_bf16 v[124:127], v[188:191], v[232:235], v[124:127]
	s_setprio 0
	s_lshr_b32 s51, s90, 6
	s_lshl_b32 s51, s51, 7
	s_and_b32 s17, s90, 63
	s_lshl_b32 s17, s17, 8
	s_mov_b32 s16, 0x1b00
	s_mov_b32 s18, 0
	s_mov_b32 s19, 0
	s_cmp_lt_u32 s51, 0xd80
	s_cbranch_scc1 .Lbig_reg
	s_mov_b32 s16, 0x1900
	s_mov_b32 s18, 0x6c00000
	s_mov_b32 s19, 0xd80
	s_cmp_lt_u32 s51, 0x1a00
	s_cbranch_scc1 .Lbig_reg
	s_mov_b32 s16, 0x2000
	s_mov_b32 s18, 0xd000000
	s_mov_b32 s19, 0x1a00
